# remaining read-once streams non-temporal too: P4's f32 x residual loads and the raw f32 weight loads of the deferred conversion
# speedup vs baseline: 1.0130x; 1.0032x over previous
; __device__ __forceinline__ unsigned cvt_pk_bf16(float lo, float hi) { unsigned r; asm volatile("v_cvt_pk_bf16_f32 %0, %1, %2" : "=v"(r) : "v"(lo), "v"(hi)); return r; }
;     __device__ __forceinline__ void tail(const f32x4& b0, const f32x4& b1, const f32x4& a0, const f32x4& a1, bf16_t* dst, float& s) const {
;         const f32x4 o0 = b0 + a0, o1 = b1 + a1;
;         s += ((o0[0] * o0[0] + o0[1] * o0[1]) + (o0[2] * o0[2] + o0[3] * o0[3])) + ((o1[0] * o1[0] + o1[1] * o1[1]) + (o1[2] * o1[2] + o1[3] * o1[3]));
;         u32x4 w; w.x = cvt_pk_bf16(o0[0], o0[1]); w.y = cvt_pk_bf16(o0[2], o0[3]); w.z = cvt_pk_bf16(o1[0], o1[1]); w.w = cvt_pk_bf16(o1[2], o1[3]);
;         *(u32x4*)dst = w;
;     __device__ __forceinline__ void operator()(const f32x4 (&acc)[2][2][4][2], const Unit& u, int wr, int wc, int fr, int fq) const {
;     ...
;             EPI_LDQ(qa0, qa1, 0); EPI_LDQ(qb0, qb1, 1); asm volatile("" ::: "memory");
;             EPI_DOQ(qa0, qa1, 0); EPI_LDQ(qa0, qa1, 2); asm volatile("" ::: "memory");
;             EPI_DOQ(qb0, qb1, 1); EPI_LDQ(qb0, qb1, 3); asm volatile("" ::: "memory");
;             EPI_DOQ(qa0, qa1, 2); asm volatile("" ::: "memory");
;             EPI_DOQ(qb0, qb1, 3);
.Lp4_kdone:
	s_waitcnt lgkmcnt(0)
	s_nop 7
	s_nop 7
	v_and_b32_e32 v254, 63, v185
	v_and_b32_e32 v255, 15, v254
	v_lshrrev_b32_e32 v233, 4, v254
	s_lshl_b32 s40, s37, 6
	v_add_u32_e32 v255, s40, v255
	v_lshlrev_b32_e32 v230, 2, v255
	v_lshlrev_b32_e32 v228, 13, v255
	v_lshlrev_b32_e32 v229, 12, v255
	s_lshl_b32 s41, s38, 7
	v_lshl_add_u32 v228, v233, 5, v228
	v_add_u32_e32 v228, s41, v228
	s_lshl_b32 s41, s38, 6
	v_lshl_add_u32 v229, v233, 4, v229
	v_add_u32_e32 v229, s41, v229
	v_xor_b32_e32 v231, 16, v254
	v_lshlrev_b32_e32 v231, 2, v231
	v_xor_b32_e32 v232, 32, v254
	v_lshlrev_b32_e32 v232, 2, v232
	v_readlane_b32 s48, v244, 12
	v_readlane_b32 s49, v244, 13
	s_lshl_b32 s40, s17, 21
	s_lshl_b32 s41, s18, 10
	s_add_u32 s40, s40, s41
	s_add_u32 s48, s48, s40
	s_addc_u32 s49, s49, 0
	s_lshl_b32 s40, s17, 10
	s_add_u32 s50, s76, s40
	s_addc_u32 s51, s77, 0
	s_lshl_b32 s40, s17, 20
	s_lshl_b32 s41, s18, 9
	s_add_u32 s40, s40, s41
	s_add_u32 s52, s76, 0x6800000
	s_addc_u32 s53, s77, 0
	s_add_u32 s52, s52, s40
	s_addc_u32 s53, s53, 0
	v_add_u32_e32 v233, 0x0, v228
	global_load_dwordx4 v[128:131], v233, s[48:49] offset:0 nt
	global_load_dwordx4 v[132:135], v233, s[48:49] offset:16 nt
	global_load_dwordx4 v[136:139], v233, s[48:49] offset:512 nt
	global_load_dwordx4 v[140:143], v233, s[48:49] offset:528 nt
	v_add_u32_e32 v233, 0x20000, v228
	global_load_dwordx4 v[144:147], v233, s[48:49] offset:0 nt
	global_load_dwordx4 v[148:151], v233, s[48:49] offset:16 nt
	global_load_dwordx4 v[152:155], v233, s[48:49] offset:512 nt
	global_load_dwordx4 v[156:159], v233, s[48:49] offset:528 nt
	v_add_u32_e32 v233, 0x40000, v228
	global_load_dwordx4 v[160:163], v233, s[48:49] offset:0 nt
	global_load_dwordx4 v[164:167], v233, s[48:49] offset:16 nt
	global_load_dwordx4 v[168:171], v233, s[48:49] offset:512 nt
	global_load_dwordx4 v[172:175], v233, s[48:49] offset:528 nt
	v_add_u32_e32 v233, 0x60000, v228
	global_load_dwordx4 v[176:179], v233, s[48:49] offset:0 nt
	global_load_dwordx4 v[180:183], v233, s[48:49] offset:16 nt
	global_load_dwordx4 v[188:191], v233, s[48:49] offset:512 nt
	global_load_dwordx4 v[192:195], v233, s[48:49] offset:528 nt
	v_add_u32_e32 v233, 0x100000, v228
	global_load_dwordx4 v[196:199], v233, s[48:49] offset:0 nt
	global_load_dwordx4 v[200:203], v233, s[48:49] offset:16 nt
	global_load_dwordx4 v[204:207], v233, s[48:49] offset:512 nt
	global_load_dwordx4 v[208:211], v233, s[48:49] offset:528 nt
	v_add_u32_e32 v233, 0x120000, v228
	global_load_dwordx4 v[212:215], v233, s[48:49] offset:0 nt
	global_load_dwordx4 v[216:219], v233, s[48:49] offset:16 nt
	global_load_dwordx4 v[220:223], v233, s[48:49] offset:512 nt
	global_load_dwordx4 v[224:227], v233, s[48:49] offset:528 nt
	s_waitcnt vmcnt(16)
	v_add_f32_e32 v0, v0, v128
	v_mul_f32_e32 v235, v0, v0
	v_add_f32_e32 v1, v1, v129
	v_fmac_f32_e32 v235, v1, v1
	v_add_f32_e32 v2, v2, v130
	v_fmac_f32_e32 v235, v2, v2
	v_add_f32_e32 v3, v3, v131
	v_fmac_f32_e32 v235, v3, v3
	v_add_f32_e32 v4, v4, v132
	v_fmac_f32_e32 v235, v4, v4
	v_add_f32_e32 v5, v5, v133
	v_fmac_f32_e32 v235, v5, v5
	v_add_f32_e32 v6, v6, v134
	v_fmac_f32_e32 v235, v6, v6
	v_add_f32_e32 v7, v7, v135
	v_fmac_f32_e32 v235, v7, v7
	v_add_f32_e32 v32, v32, v136
	v_fmac_f32_e32 v235, v32, v32
	v_add_f32_e32 v33, v33, v137
	v_fmac_f32_e32 v235, v33, v33
	v_add_f32_e32 v34, v34, v138
	v_fmac_f32_e32 v235, v34, v34
	v_add_f32_e32 v35, v35, v139
	v_fmac_f32_e32 v235, v35, v35
	v_add_f32_e32 v36, v36, v140
	v_fmac_f32_e32 v235, v36, v36
	v_add_f32_e32 v37, v37, v141
	v_fmac_f32_e32 v235, v37, v37
	v_add_f32_e32 v38, v38, v142
	v_fmac_f32_e32 v235, v38, v38
	v_add_f32_e32 v39, v39, v143
	v_fmac_f32_e32 v235, v39, v39
	v_add_u32_e32 v234, 0x0, v229
	v_cvt_pk_bf16_f32 v0, v0, v1
	v_cvt_pk_bf16_f32 v1, v2, v3
	v_cvt_pk_bf16_f32 v2, v4, v5
	v_cvt_pk_bf16_f32 v3, v6, v7
	s_nop 1
	global_store_dwordx4 v234, v[0:3], s[52:53] offset:0
	v_cvt_pk_bf16_f32 v32, v32, v33
	v_cvt_pk_bf16_f32 v33, v34, v35
	v_cvt_pk_bf16_f32 v34, v36, v37
	v_cvt_pk_bf16_f32 v35, v38, v39
	s_nop 1
	global_store_dwordx4 v234, v[32:35], s[52:53] offset:256
	v_mov_b32_e32 v36, v235
	v_add_f32_e32 v8, v8, v144
	v_mul_f32_e32 v235, v8, v8
	v_add_f32_e32 v9, v9, v145
	v_fmac_f32_e32 v235, v9, v9
	v_add_f32_e32 v10, v10, v146
	v_fmac_f32_e32 v235, v10, v10
	v_add_f32_e32 v11, v11, v147
	v_fmac_f32_e32 v235, v11, v11
	v_add_f32_e32 v12, v12, v148
	v_fmac_f32_e32 v235, v12, v12
	v_add_f32_e32 v13, v13, v149
	v_fmac_f32_e32 v235, v13, v13
	v_add_f32_e32 v14, v14, v150
	v_fmac_f32_e32 v235, v14, v14
	v_add_f32_e32 v15, v15, v151
	v_fmac_f32_e32 v235, v15, v15
	v_add_f32_e32 v40, v40, v152
	v_fmac_f32_e32 v235, v40, v40
	v_add_f32_e32 v41, v41, v153
	v_fmac_f32_e32 v235, v41, v41
	v_add_f32_e32 v42, v42, v154
	v_fmac_f32_e32 v235, v42, v42
	v_add_f32_e32 v43, v43, v155
	v_fmac_f32_e32 v235, v43, v43
	v_add_f32_e32 v44, v44, v156
	v_fmac_f32_e32 v235, v44, v44
	v_add_f32_e32 v45, v45, v157
	v_fmac_f32_e32 v235, v45, v45
	v_add_f32_e32 v46, v46, v158
	v_fmac_f32_e32 v235, v46, v46
	v_add_f32_e32 v47, v47, v159
	v_fmac_f32_e32 v235, v47, v47
	v_add_u32_e32 v234, 0x10000, v229
	v_cvt_pk_bf16_f32 v8, v8, v9
	v_cvt_pk_bf16_f32 v9, v10, v11
	v_cvt_pk_bf16_f32 v10, v12, v13
	v_cvt_pk_bf16_f32 v11, v14, v15
	s_nop 1
	global_store_dwordx4 v234, v[8:11], s[52:53] offset:0
	v_cvt_pk_bf16_f32 v40, v40, v41
	v_cvt_pk_bf16_f32 v41, v42, v43
	v_cvt_pk_bf16_f32 v42, v44, v45
	v_cvt_pk_bf16_f32 v43, v46, v47
	s_nop 1
	global_store_dwordx4 v234, v[40:43], s[52:53] offset:256
	v_mov_b32_e32 v44, v235
	v_add_u32_e32 v233, 0x140000, v228
	global_load_dwordx4 v[128:131], v233, s[48:49] offset:0 nt
	global_load_dwordx4 v[132:135], v233, s[48:49] offset:16 nt
	global_load_dwordx4 v[136:139], v233, s[48:49] offset:512 nt
	global_load_dwordx4 v[140:143], v233, s[48:49] offset:528 nt
	v_add_u32_e32 v233, 0x160000, v228
	global_load_dwordx4 v[144:147], v233, s[48:49] offset:0 nt
	global_load_dwordx4 v[148:151], v233, s[48:49] offset:16 nt
	global_load_dwordx4 v[152:155], v233, s[48:49] offset:512 nt
	global_load_dwordx4 v[156:159], v233, s[48:49] offset:528 nt
	s_waitcnt vmcnt(20)
; __device__ __forceinline__ unsigned cvt_pk_bf16(float lo, float hi) { unsigned r; asm volatile("v_cvt_pk_bf16_f32 %0, %1, %2" : "=v"(r) : "v"(lo), "v"(hi)); return r; }
;     __device__ __forceinline__ void tail(const f32x4& b0, const f32x4& b1, const f32x4& a0, const f32x4& a1, bf16_t* dst, float& s) const {
;         const f32x4 o0 = b0 + a0, o1 = b1 + a1;
;         s += ((o0[0] * o0[0] + o0[1] * o0[1]) + (o0[2] * o0[2] + o0[3] * o0[3])) + ((o1[0] * o1[0] + o1[1] * o1[1]) + (o1[2] * o1[2] + o1[3] * o1[3]));
;         u32x4 w; w.x = cvt_pk_bf16(o0[0], o0[1]); w.y = cvt_pk_bf16(o0[2], o0[3]); w.z = cvt_pk_bf16(o1[0], o1[1]); w.w = cvt_pk_bf16(o1[2], o1[3]);
;         *(u32x4*)dst = w;
	v_add_f32_e32 v16, v16, v160
	v_mul_f32_e32 v235, v16, v16
	v_add_f32_e32 v17, v17, v161
	v_fmac_f32_e32 v235, v17, v17
	v_add_f32_e32 v18, v18, v162
	v_fmac_f32_e32 v235, v18, v18
	v_add_f32_e32 v19, v19, v163
	v_fmac_f32_e32 v235, v19, v19
	v_add_f32_e32 v20, v20, v164
	v_fmac_f32_e32 v235, v20, v20
	v_add_f32_e32 v21, v21, v165
	v_fmac_f32_e32 v235, v21, v21
	v_add_f32_e32 v22, v22, v166
	v_fmac_f32_e32 v235, v22, v22
	v_add_f32_e32 v23, v23, v167
	v_fmac_f32_e32 v235, v23, v23
	v_add_f32_e32 v48, v48, v168
	v_fmac_f32_e32 v235, v48, v48
	v_add_f32_e32 v49, v49, v169
	v_fmac_f32_e32 v235, v49, v49
	v_add_f32_e32 v50, v50, v170
	v_fmac_f32_e32 v235, v50, v50
	v_add_f32_e32 v51, v51, v171
	v_fmac_f32_e32 v235, v51, v51
	v_add_f32_e32 v52, v52, v172
	v_fmac_f32_e32 v235, v52, v52
	v_add_f32_e32 v53, v53, v173
	v_fmac_f32_e32 v235, v53, v53
	v_add_f32_e32 v54, v54, v174
	v_fmac_f32_e32 v235, v54, v54
	v_add_f32_e32 v55, v55, v175
	v_fmac_f32_e32 v235, v55, v55
	v_add_u32_e32 v234, 0x20000, v229
	v_cvt_pk_bf16_f32 v16, v16, v17
	v_cvt_pk_bf16_f32 v17, v18, v19
	v_cvt_pk_bf16_f32 v18, v20, v21
	v_cvt_pk_bf16_f32 v19, v22, v23
	s_nop 1
	global_store_dwordx4 v234, v[16:19], s[52:53] offset:0
	v_cvt_pk_bf16_f32 v48, v48, v49
	v_cvt_pk_bf16_f32 v49, v50, v51
	v_cvt_pk_bf16_f32 v50, v52, v53
	v_cvt_pk_bf16_f32 v51, v54, v55
	s_nop 1
	global_store_dwordx4 v234, v[48:51], s[52:53] offset:256
	v_mov_b32_e32 v52, v235
	v_add_f32_e32 v24, v24, v176
	v_mul_f32_e32 v235, v24, v24
	v_add_f32_e32 v25, v25, v177
	v_fmac_f32_e32 v235, v25, v25
	v_add_f32_e32 v26, v26, v178
	v_fmac_f32_e32 v235, v26, v26
	v_add_f32_e32 v27, v27, v179
	v_fmac_f32_e32 v235, v27, v27
	v_add_f32_e32 v28, v28, v180
	v_fmac_f32_e32 v235, v28, v28
	v_add_f32_e32 v29, v29, v181
	v_fmac_f32_e32 v235, v29, v29
	v_add_f32_e32 v30, v30, v182
	v_fmac_f32_e32 v235, v30, v30
	v_add_f32_e32 v31, v31, v183
	v_fmac_f32_e32 v235, v31, v31
	v_add_f32_e32 v56, v56, v188
	v_fmac_f32_e32 v235, v56, v56
	v_add_f32_e32 v57, v57, v189
	v_fmac_f32_e32 v235, v57, v57
	v_add_f32_e32 v58, v58, v190
	v_fmac_f32_e32 v235, v58, v58
	v_add_f32_e32 v59, v59, v191
	v_fmac_f32_e32 v235, v59, v59
	v_add_f32_e32 v60, v60, v192
	v_fmac_f32_e32 v235, v60, v60
	v_add_f32_e32 v61, v61, v193
	v_fmac_f32_e32 v235, v61, v61
	v_add_f32_e32 v62, v62, v194
	v_fmac_f32_e32 v235, v62, v62
	v_add_f32_e32 v63, v63, v195
	v_fmac_f32_e32 v235, v63, v63
	v_add_u32_e32 v234, 0x30000, v229
	v_cvt_pk_bf16_f32 v24, v24, v25
	v_cvt_pk_bf16_f32 v25, v26, v27
	v_cvt_pk_bf16_f32 v26, v28, v29
	v_cvt_pk_bf16_f32 v27, v30, v31
	s_nop 1
	global_store_dwordx4 v234, v[24:27], s[52:53] offset:0
	v_cvt_pk_bf16_f32 v56, v56, v57
	v_cvt_pk_bf16_f32 v57, v58, v59
	v_cvt_pk_bf16_f32 v58, v60, v61
	v_cvt_pk_bf16_f32 v59, v62, v63
	s_nop 1
	global_store_dwordx4 v234, v[56:59], s[52:53] offset:256
	v_mov_b32_e32 v60, v235
	s_waitcnt vmcnt(16)
	v_add_f32_e32 v64, v64, v196
	v_mul_f32_e32 v235, v64, v64
	v_add_f32_e32 v65, v65, v197
	v_fmac_f32_e32 v235, v65, v65
	v_add_f32_e32 v66, v66, v198
	v_fmac_f32_e32 v235, v66, v66
	v_add_f32_e32 v67, v67, v199
	v_fmac_f32_e32 v235, v67, v67
	v_add_f32_e32 v68, v68, v200
	v_fmac_f32_e32 v235, v68, v68
	v_add_f32_e32 v69, v69, v201
	v_fmac_f32_e32 v235, v69, v69
	v_add_f32_e32 v70, v70, v202
	v_fmac_f32_e32 v235, v70, v70
	v_add_f32_e32 v71, v71, v203
	v_fmac_f32_e32 v235, v71, v71
	v_add_f32_e32 v96, v96, v204
	v_fmac_f32_e32 v235, v96, v96
	v_add_f32_e32 v97, v97, v205
	v_fmac_f32_e32 v235, v97, v97
	v_add_f32_e32 v98, v98, v206
	v_fmac_f32_e32 v235, v98, v98
	v_add_f32_e32 v99, v99, v207
	v_fmac_f32_e32 v235, v99, v99
	v_add_f32_e32 v100, v100, v208
	v_fmac_f32_e32 v235, v100, v100
	v_add_f32_e32 v101, v101, v209
	v_fmac_f32_e32 v235, v101, v101
	v_add_f32_e32 v102, v102, v210
	v_fmac_f32_e32 v235, v102, v102
	v_add_f32_e32 v103, v103, v211
	v_fmac_f32_e32 v235, v103, v103
	v_add_u32_e32 v234, 0x80000, v229
	v_cvt_pk_bf16_f32 v64, v64, v65
	v_cvt_pk_bf16_f32 v65, v66, v67
	v_cvt_pk_bf16_f32 v66, v68, v69
	v_cvt_pk_bf16_f32 v67, v70, v71
	s_nop 1
	global_store_dwordx4 v234, v[64:67], s[52:53] offset:0
	v_cvt_pk_bf16_f32 v96, v96, v97
	v_cvt_pk_bf16_f32 v97, v98, v99
	v_cvt_pk_bf16_f32 v98, v100, v101
	v_cvt_pk_bf16_f32 v99, v102, v103
	s_nop 1
	global_store_dwordx4 v234, v[96:99], s[52:53] offset:256
	v_mov_b32_e32 v100, v235
	v_add_f32_e32 v72, v72, v212
	v_mul_f32_e32 v235, v72, v72
	v_add_f32_e32 v73, v73, v213
	v_fmac_f32_e32 v235, v73, v73
	v_add_f32_e32 v74, v74, v214
	v_fmac_f32_e32 v235, v74, v74
	v_add_f32_e32 v75, v75, v215
	v_fmac_f32_e32 v235, v75, v75
	v_add_f32_e32 v76, v76, v216
	v_fmac_f32_e32 v235, v76, v76
	v_add_f32_e32 v77, v77, v217
	v_fmac_f32_e32 v235, v77, v77
	v_add_f32_e32 v78, v78, v218
	v_fmac_f32_e32 v235, v78, v78
	v_add_f32_e32 v79, v79, v219
	v_fmac_f32_e32 v235, v79, v79
	v_add_f32_e32 v104, v104, v220
	v_fmac_f32_e32 v235, v104, v104
	v_add_f32_e32 v105, v105, v221
	v_fmac_f32_e32 v235, v105, v105
	v_add_f32_e32 v106, v106, v222
	v_fmac_f32_e32 v235, v106, v106
	v_add_f32_e32 v107, v107, v223
	v_fmac_f32_e32 v235, v107, v107
	v_add_f32_e32 v108, v108, v224
	v_fmac_f32_e32 v235, v108, v108
	v_add_f32_e32 v109, v109, v225
	v_fmac_f32_e32 v235, v109, v109
	v_add_f32_e32 v110, v110, v226
	v_fmac_f32_e32 v235, v110, v110
	v_add_f32_e32 v111, v111, v227
	v_fmac_f32_e32 v235, v111, v111
	v_add_u32_e32 v234, 0x90000, v229
	v_cvt_pk_bf16_f32 v72, v72, v73
	v_cvt_pk_bf16_f32 v73, v74, v75
	v_cvt_pk_bf16_f32 v74, v76, v77
	v_cvt_pk_bf16_f32 v75, v78, v79
	s_nop 1
	global_store_dwordx4 v234, v[72:75], s[52:53] offset:0
	v_cvt_pk_bf16_f32 v104, v104, v105
	v_cvt_pk_bf16_f32 v105, v106, v107
	v_cvt_pk_bf16_f32 v106, v108, v109
	v_cvt_pk_bf16_f32 v107, v110, v111
	s_nop 1
	global_store_dwordx4 v234, v[104:107], s[52:53] offset:256
	v_mov_b32_e32 v108, v235
	s_waitcnt vmcnt(8)
; template <class Epi, class Sched, bool ALIGN_EPI = false, bool SP2 = false>
; __device__ __forceinline__ void gemm_phase(PG8_LAS unsigned char* lds, const Gemm g, const Sched& S, const Epi& E) {
;     ...
;         if constexpr (!Epi::AFTER_DRAIN) { E(acc, cur, wr, wc, fr, fq); S.done(cur); }
;         if (!has_next) break;
; #pragma unroll
;         for (int a = 0; a < 2; ++a)
; #pragma unroll
;             for (int b = 0; b < 2; ++b)
; #pragma unroll
;                 for (int m = 0; m < 4; ++m)
; #pragma unroll
;                     for (int n = 0; n < 2; ++n) acc[a][b][m][n] = (f32x4){0.f, 0.f, 0.f, 0.f};
;         cur = nxt; cA = nA; cB = nB; ++ui;
	v_add_f32_e32 v80, v80, v128
	v_mul_f32_e32 v235, v80, v80
	v_add_f32_e32 v81, v81, v129
	v_fmac_f32_e32 v235, v81, v81
	v_add_f32_e32 v82, v82, v130
	v_fmac_f32_e32 v235, v82, v82
	v_add_f32_e32 v83, v83, v131
	v_fmac_f32_e32 v235, v83, v83
	v_add_f32_e32 v84, v84, v132
	v_fmac_f32_e32 v235, v84, v84
	v_add_f32_e32 v85, v85, v133
	v_fmac_f32_e32 v235, v85, v85
	v_add_f32_e32 v86, v86, v134
	v_fmac_f32_e32 v235, v86, v86
	v_add_f32_e32 v87, v87, v135
	v_fmac_f32_e32 v235, v87, v87
	v_add_f32_e32 v112, v112, v136
	v_fmac_f32_e32 v235, v112, v112
	v_add_f32_e32 v113, v113, v137
	v_fmac_f32_e32 v235, v113, v113
	v_add_f32_e32 v114, v114, v138
	v_fmac_f32_e32 v235, v114, v114
	v_add_f32_e32 v115, v115, v139
	v_fmac_f32_e32 v235, v115, v115
	v_add_f32_e32 v116, v116, v140
	v_fmac_f32_e32 v235, v116, v116
	v_add_f32_e32 v117, v117, v141
	v_fmac_f32_e32 v235, v117, v117
	v_add_f32_e32 v118, v118, v142
	v_fmac_f32_e32 v235, v118, v118
	v_add_f32_e32 v119, v119, v143
	v_fmac_f32_e32 v235, v119, v119
	v_add_u32_e32 v234, 0xa0000, v229
	v_cvt_pk_bf16_f32 v80, v80, v81
	v_cvt_pk_bf16_f32 v81, v82, v83
	v_cvt_pk_bf16_f32 v82, v84, v85
	v_cvt_pk_bf16_f32 v83, v86, v87
	s_nop 1
	global_store_dwordx4 v234, v[80:83], s[52:53] offset:0
	v_cvt_pk_bf16_f32 v112, v112, v113
	v_cvt_pk_bf16_f32 v113, v114, v115
	v_cvt_pk_bf16_f32 v114, v116, v117
	v_cvt_pk_bf16_f32 v115, v118, v119
	s_nop 1
	global_store_dwordx4 v234, v[112:115], s[52:53] offset:256
	v_mov_b32_e32 v116, v235
	v_add_f32_e32 v88, v88, v144
	v_mul_f32_e32 v235, v88, v88
	v_add_f32_e32 v89, v89, v145
	v_fmac_f32_e32 v235, v89, v89
	v_add_f32_e32 v90, v90, v146
	v_fmac_f32_e32 v235, v90, v90
	v_add_f32_e32 v91, v91, v147
	v_fmac_f32_e32 v235, v91, v91
	v_add_f32_e32 v92, v92, v148
	v_fmac_f32_e32 v235, v92, v92
	v_add_f32_e32 v93, v93, v149
	v_fmac_f32_e32 v235, v93, v93
	v_add_f32_e32 v94, v94, v150
	v_fmac_f32_e32 v235, v94, v94
	v_add_f32_e32 v95, v95, v151
	v_fmac_f32_e32 v235, v95, v95
	v_add_f32_e32 v120, v120, v152
	v_fmac_f32_e32 v235, v120, v120
	v_add_f32_e32 v121, v121, v153
	v_fmac_f32_e32 v235, v121, v121
	v_add_f32_e32 v122, v122, v154
	v_fmac_f32_e32 v235, v122, v122
	v_add_f32_e32 v123, v123, v155
	v_fmac_f32_e32 v235, v123, v123
	v_add_f32_e32 v124, v124, v156
	v_fmac_f32_e32 v235, v124, v124
	v_add_f32_e32 v125, v125, v157
	v_fmac_f32_e32 v235, v125, v125
	v_add_f32_e32 v126, v126, v158
	v_fmac_f32_e32 v235, v126, v126
	v_add_f32_e32 v127, v127, v159
	v_fmac_f32_e32 v235, v127, v127
	v_add_u32_e32 v234, 0xb0000, v229
	v_cvt_pk_bf16_f32 v88, v88, v89
	v_cvt_pk_bf16_f32 v89, v90, v91
	v_cvt_pk_bf16_f32 v90, v92, v93
	v_cvt_pk_bf16_f32 v91, v94, v95
	s_nop 1
	global_store_dwordx4 v234, v[88:91], s[52:53] offset:0
	v_cvt_pk_bf16_f32 v120, v120, v121
	v_cvt_pk_bf16_f32 v121, v122, v123
	v_cvt_pk_bf16_f32 v122, v124, v125
	v_cvt_pk_bf16_f32 v123, v126, v127
	s_nop 1
	global_store_dwordx4 v234, v[120:123], s[52:53] offset:256
	v_mov_b32_e32 v124, v235
	ds_bpermute_b32 v128, v231, v36
	ds_bpermute_b32 v132, v231, v44
	ds_bpermute_b32 v136, v231, v52
	ds_bpermute_b32 v140, v231, v60
	ds_bpermute_b32 v144, v231, v100
	ds_bpermute_b32 v148, v231, v108
	ds_bpermute_b32 v152, v231, v116
	ds_bpermute_b32 v156, v231, v124
	s_waitcnt lgkmcnt(0)
	v_add_f32_e32 v36, v36, v128
	v_add_f32_e32 v44, v44, v132
	v_add_f32_e32 v52, v52, v136
	v_add_f32_e32 v60, v60, v140
	v_add_f32_e32 v100, v100, v144
	v_add_f32_e32 v108, v108, v148
	v_add_f32_e32 v116, v116, v152
	v_add_f32_e32 v124, v124, v156
	ds_bpermute_b32 v128, v232, v36
	ds_bpermute_b32 v132, v232, v44
	ds_bpermute_b32 v136, v232, v52
	ds_bpermute_b32 v140, v232, v60
	ds_bpermute_b32 v144, v232, v100
	ds_bpermute_b32 v148, v232, v108
	ds_bpermute_b32 v152, v232, v116
	ds_bpermute_b32 v156, v232, v124
	s_waitcnt lgkmcnt(0)
	v_add_f32_e32 v36, v36, v128
	v_add_f32_e32 v44, v44, v132
	v_add_f32_e32 v52, v52, v136
	v_add_f32_e32 v60, v60, v140
	v_add_f32_e32 v100, v100, v144
	v_add_f32_e32 v108, v108, v148
	v_add_f32_e32 v116, v116, v152
	v_add_f32_e32 v124, v124, v156
	s_mov_b64 exec, 0xffff
	global_atomic_add_f32 v230, v36, s[50:51] offset:0
	global_atomic_add_f32 v230, v44, s[50:51] offset:64
	global_atomic_add_f32 v230, v52, s[50:51] offset:128
	global_atomic_add_f32 v230, v60, s[50:51] offset:192
	global_atomic_add_f32 v230, v100, s[50:51] offset:512
	global_atomic_add_f32 v230, v108, s[50:51] offset:576
	global_atomic_add_f32 v230, v116, s[50:51] offset:640
	global_atomic_add_f32 v230, v124, s[50:51] offset:704
	s_mov_b64 exec, -1
	s_nop 1
	s_cmp_eq_u32 s19, 0
	s_cbranch_scc1 .Lp4_done
	s_mov_b32 s17, s20
	s_mov_b32 s18, s21
	s_mov_b64 s[22:23], s[26:27]
	s_mov_b64 s[24:25], s[28:29]
	s_add_u32 s16, s16, 1
	s_branch .Lp4_unit
